# attention: the last key-pair step of a unit loads the next unit's first key/value pair instead of a duplicate of its own last pair (no K/V loads at unit start)
# speedup vs baseline: 1.0063x; 1.0010x over previous
.Lqpf_unit:
	s_sub_i32 s13, s13, s12
	s_add_i32 s13, s13, 4
	s_ashr_i32 s20, s13, 1
	ds_write_b128 v175, v[220:223]
	ds_write_b128 v175, v[224:227] offset:1152
	ds_write_b128 v175, v[228:231] offset:2304
	ds_write_b128 v175, v[232:235] offset:3456
	s_branch .Latt_join

.LBB0_1073:
	s_mov_b32 s26, s23
	s_and_b32 s24, s22, 0x80
	s_add_i32 s23, s23, 1
	s_cmp_lt_i32 s23, s20
	s_cselect_b32 s26, s23, s26
	s_lshl_b32 s26, s26, 1
	s_add_i32 s26, s26, s12
	s_cmp_eq_u32 s23, s20
	s_cselect_b32 s27, 1, 0
	s_cmp_lg_u32 s16, 7
	s_cselect_b32 s27, s27, 0
	s_add_i32 s28, s16, 1
	s_or_b32 s28, s28, s14
	s_lshl_b32 s29, s28, 2
	s_add_i32 s29, s29, -8
	s_cmp_gt_u32 s28, 1
	s_cselect_b32 s28, s29, 0
	s_cmp_lg_u32 s27, 0
	s_cselect_b32 s26, s28, s26
	s_ashr_i32 s27, s26, 31
	s_mul_i32 s25, s24, 0x90
	s_mulk_i32 s24, 0xc0
	s_lshl_b64 s[28:29], s[26:27], 17
	s_or_b32 s26, s26, 1
	v_add_u32_e32 v32, s25, v132
	v_add_u32_e32 v33, s24, v134
	s_ashr_i32 s27, s26, 31
	s_waitcnt vmcnt(0)
	ds_write_b128 v32, v[124:127]
	ds_write_b128 v33, v[120:123] offset:36864
	ds_write_b128 v32, v[116:119] offset:9216
	ds_write_b128 v33, v[112:115] offset:49152
	v_lshl_add_u64 v[32:33], v[128:129], 0, s[28:29]
	s_lshl_b64 s[26:27], s[26:27], 17
	v_lshl_add_u64 v[34:35], v[130:131], 0, s[28:29]
	global_load_dwordx4 v[124:127], v[32:33], off
	global_load_dwordx4 v[120:123], v[34:35], off
	v_lshl_add_u64 v[32:33], v[128:129], 0, s[26:27]
	v_lshl_add_u64 v[34:35], v[130:131], 0, s[26:27]
	global_load_dwordx4 v[116:119], v[32:33], off
	global_load_dwordx4 v[112:115], v[34:35], off
	s_cmp_lg_u32 s23, s20
	s_cbranch_scc1 .Lqpf_skip
	s_cmp_eq_u32 s16, 7
	s_cbranch_scc1 .Lqpf_skip
	v_lshl_add_u64 v[218:219], v[138:139], 0, s[30:31]
	v_lshl_add_u64 v[236:237], v[218:219], 0, s[4:5]
	v_lshl_add_u64 v[238:239], v[218:219], 0, s[6:7]
	v_lshl_add_u64 v[240:241], v[218:219], 0, s[8:9]
	global_load_dwordx4 v[220:223], v[218:219], off
	global_load_dwordx4 v[224:227], v[236:237], off
	global_load_dwordx4 v[228:231], v[238:239], off
	global_load_dwordx4 v[232:235], v[240:241], off
